# Hyena filter generation rewritten: w3 slice interleaved [j][q] in LDS, hdn row loaded once per t, 128 v_pk_fma with broadcast h_j (no operand shuffles, 2.4x fewer instructions)
# baseline (speedup 1.0000x reference)
; __device__ __forceinline__ void hy_conv_item(const Ctx& C, int l, int c) {
;     ...
;     bf16_t* G10 = (bf16_t*)C.lds; bf16_t* G11 = G10 + GLEN; bf16_t* G20 = G11 + GLEN; bf16_t* G21 = G20 + GLEN; bf16_t* U = G21 + GLEN;
;     float* red = (float*)(C.lds + (size_t)(4 * GLEN + 8 * UP) * 2); float* w3s = red + 64;
;     for (int i = tid; i < 2 * GLEN; i += NTHR) ((unsigned*)G10)[i] = 0u;
;     if (tid < 256) { const int q = tid >> 6, j = tid & 63; const int col = (q >> 1) * 512 + (q & 1) * 256 + c; w3s[q * 64 + j] = C.P->in[19][((size_t)l * 64 + j) * 1024 + col]; }
;     __syncthreads();
;     float ss[4] = {0.f, 0.f, 0.f, 0.f};
;     const float adelta = 3.0701134573253945f + (float)c * ((15.350567286626972f - 3.0701134573253945f) / 255.f);
;     const float* hdn = C.fp(OFF_HDN);
;     float* hft = (float*)U;
; #pragma unroll 1
;     for (int k = 0; k < 8; ++k) { const int t = tid + NTHR * k; const f32x4* hr = (const f32x4*)(hdn + (size_t)t * 64);
;         float a0 = 0.f, a1 = 0.f, a2 = 0.f, a3 = 0.f;
; #pragma unroll 1
;         for (int j8 = 0; j8 < 16; j8 += 8) {
;         f32x4 hrow[8];
; #pragma unroll
;         for (int j4 = 0; j4 < 8; ++j4) hrow[j4] = hr[j8 + j4];
; #pragma unroll
;         for (int jj4 = 0; jj4 < 8; ++jj4) { const f32x4 hv = hrow[jj4]; const int j4 = j8 + jj4;
;             const f32x4 q0 = *(const f32x4*)(w3s + 4 * j4), q1 = *(const f32x4*)(w3s + 64 + 4 * j4), q2 = *(const f32x4*)(w3s + 128 + 4 * j4), q3 = *(const f32x4*)(w3s + 192 + 4 * j4);
;             a0 += hv.x * q0.x + hv.y * q0.y + hv.z * q0.z + hv.w * q0.w; a1 += hv.x * q1.x + hv.y * q1.y + hv.z * q1.z + hv.w * q1.w;
;             a2 += hv.x * q2.x + hv.y * q2.y + hv.z * q2.z + hv.w * q2.w; a3 += hv.x * q3.x + hv.y * q3.y + hv.z * q3.z + hv.w * q3.w; } }
;         const float dec = __expf(-((float)t / 4095.f) * adelta);
;         a0 *= dec; a1 *= dec; a2 *= dec; a3 *= dec;
;         hft[t] = a0; hft[4096 + t] = a1; hft[8192 + t] = a2; hft[12288 + t] = a3;
;         ss[0] += a0 * a0; ss[1] += a1 * a1; ss[2] += a2 * a2; ss[3] += a3 * a3; }
; #pragma unroll
;     for (int q = 0; q < 4; ++q) { const float s_ = wave_sum(ss[q]); if (lane == 0) red[w * 4 + q] = s_; }
;     __syncthreads();
;     float sc[4];
; #pragma unroll
;     for (int q = 0; q < 4; ++q) { float s_ = 0.f; for (int ww = 0; ww < 8; ++ww) s_ += red[ww * 4 + q]; sc[q] = rsqrtf(s_ + 1e-6f); }
; #pragma unroll 1
.Lmy_gs_poll_4:
.LBB0_602:
	s_or_b64 exec, exec, s[0:1]
	s_waitcnt lgkmcnt(0)
	v_mov_b32_e32 v0, v224
	s_mov_b64 s[0:1], 0
	v_readlane_b32 s6, v253, 28
	s_barrier
	v_mov_b32_e32 v114, v224
	v_readlane_b32 s7, v253, 29
	s_mov_b64 s[0:1], 0
	v_readfirstlane_b32 s4, v114
	s_and_b64 vcc, exec, s[6:7]
	s_cbranch_vccz .LBB0_639
	v_and_b32_e32 v0, 63, v114
	s_ashr_i32 s8, s4, 6
	s_movk_i32 s4, 0x4400
	v_cmp_gt_i32_e64 s[42:43], s4, v114
	s_movk_i32 s4, 0x100
	v_lshlrev_b32_e32 v1, 10, v114
	v_cmp_eq_u32_e64 s[46:47], 0, v0
	v_lshlrev_b32_e32 v0, 3, v114
	v_cmp_gt_i32_e64 s[44:45], s4, v114
	v_and_b32_e32 v1, 0xfc00, v1
	v_readlane_b32 s4, v254, 59
	v_and_b32_e32 v16, 0xff8, v0
	v_ashrrev_i32_e32 v0, 9, v114
	v_lshl_or_b32 v64, s4, 16, v1
	v_ashrrev_i32_e32 v1, 31, v0
	v_lshlrev_b64 v[90:91], 13, v[0:1]
	v_add_u32_e32 v1, 0x200, v114
	v_ashrrev_i32_e32 v2, 9, v1
	v_add_u32_e32 v1, 0x400, v114
	v_ashrrev_i32_e32 v4, 9, v1
	v_add_u32_e32 v1, 0x600, v114
	v_ashrrev_i32_e32 v6, 9, v1
	v_add_u32_e32 v1, 0x800, v114
	v_ashrrev_i32_e32 v8, 9, v1
	v_add_u32_e32 v1, 0xa00, v114
	v_ashrrev_i32_e32 v10, 9, v1
	v_add_u32_e32 v1, 0xc00, v114
	v_ashrrev_i32_e32 v12, 9, v1
	v_add_u32_e32 v1, 0xe00, v114
	v_ashrrev_i32_e32 v14, 9, v1
	v_sub_u32_e32 v1, 0x11f0, v16
	v_mul_i32_i24_e32 v0, 0x2810, v0
	v_lshlrev_b32_e32 v1, 1, v1
	v_readlane_b32 s10, v254, 37
	s_add_u32 s0, s24, s0
	s_addc_u32 s1, s25, s1
	v_add3_u32 v118, s10, v0, v1
	v_mul_i32_i24_e32 v0, 0x2810, v2
	v_add3_u32 v119, s10, v0, v1
	v_mul_i32_i24_e32 v0, 0x2810, v4
	v_add3_u32 v120, s10, v0, v1
	v_mul_i32_i24_e32 v0, 0x2810, v6
	v_readlane_b32 s5, v254, 60
	s_add_u32 s4, s0, 0x1e780000
	v_add3_u32 v121, s10, v0, v1
	v_mul_i32_i24_e32 v0, 0x2810, v8
	s_addc_u32 s5, s1, 0
	s_lshl_b32 s12, s8, 4
	s_movk_i32 s6, 0x5020
	v_add3_u32 v122, s10, v0, v1
	v_mul_i32_i24_e32 v0, 0x2810, v10
	v_cmp_gt_i32_e64 s[48:49], s6, v114
	s_add_u32 s6, s0, 0x17000000
	v_add3_u32 v123, s10, v0, v1
	v_mul_i32_i24_e32 v0, 0x2810, v12
	s_addc_u32 s7, s1, 0
	v_ashrrev_i32_e32 v3, 31, v2
	v_add3_u32 v124, s10, v0, v1
	v_mul_i32_i24_e32 v0, 0x2810, v14
	s_lshl_b32 s8, s8, 9
	v_lshlrev_b64 v[92:93], 13, v[2:3]
	v_add3_u32 v125, s10, v0, v1
	v_lshrrev_b32_e32 v0, 2, v114
	v_and_or_b32 v2, v114, 31, s8
	v_and_b32_e32 v0, 8, v0
	v_add_u32_e32 v2, 0xf9, v2
	v_ashrrev_i32_e32 v5, 31, v4
	v_sub_u32_e32 v3, v2, v0
	v_and_b32_e32 v2, 1, v2
	s_add_i32 s9, 0, 0x4400
	v_lshlrev_b64 v[94:95], 13, v[4:5]
	v_mov_b32_e32 v4, s9
	v_cmp_eq_u32_e32 vcc, 0, v2
	v_and_b32_e32 v3, 0x7ffffffe, v3
	v_lshlrev_b32_e32 v3, 1, v3
	v_cndmask_b32_e64 v2, v4, 0, vcc
	v_lshlrev_b32_e32 v4, 5, v114
	v_bfe_u32 v1, v114, 2, 3
	v_add_u32_e32 v126, v2, v3
	v_mov_b32_e32 v2, s10
	s_movk_i32 s9, 0x2810
	v_and_b32_e32 v4, 0x60, v4
	v_readlane_b32 s68, v251, 36
	v_mad_u32_u24 v2, v1, s9, v2
	v_sub_u32_e32 v0, v4, v0
	v_readlane_b32 s74, v251, 42
	v_readlane_b32 s75, v251, 43
	v_lshl_add_u32 v127, v0, 1, v2
	v_lshrrev_b32_e32 v0, 3, v114
	v_lshl_add_u64 v[86:87], v[64:65], 2, s[74:75]
	v_lshlrev_b32_e32 v64, 1, v16
	v_ashrrev_i32_e32 v7, 31, v6
	v_and_b32_e32 v5, 4, v0
	v_lshl_add_u64 v[88:89], s[6:7], 0, v[64:65]
	v_lshlrev_b64 v[96:97], 13, v[6:7]
	v_lshlrev_b32_e32 v64, 13, v1
	v_or_b32_e32 v6, s8, v5
	v_lshl_add_u64 v[0:1], s[6:7], 0, v[64:65]
	v_sub_u32_e32 v6, v4, v6
	v_readlane_b32 s6, v254, 39
	v_lshl_add_u32 v128, v6, 1, v2
	v_xor_b32_e32 v7, 1, v221
	v_mov_b32_e32 v2, s6
	v_readlane_b32 s6, v254, 38
	s_ashr_i32 s9, s8, 31
	v_lshlrev_b32_e32 v115, 2, v114
	v_mov_b32_e32 v6, s6
	v_cndmask_b32_e32 v2, v2, v6, vcc
	v_and_b32_e32 v6, 64, v221
	v_add_u32_e32 v6, 64, v6
	v_cmp_lt_i32_e32 vcc, v7, v6
	v_add_u32_e32 v129, v2, v3
	v_lshl_add_u64 v[2:3], s[0:1], 0, v[64:65]
	v_cndmask_b32_e32 v7, v221, v7, vcc
	v_lshlrev_b32_e32 v64, 2, v7
	v_xor_b32_e32 v7, 2, v221
	v_cmp_lt_i32_e32 vcc, v7, v6
	v_ashrrev_i32_e32 v9, 31, v8
	v_ashrrev_i32_e32 v11, 31, v10
	v_cndmask_b32_e32 v7, v221, v7, vcc
	v_lshlrev_b32_e32 v130, 2, v7
	v_xor_b32_e32 v7, 4, v221
	v_cmp_lt_i32_e32 vcc, v7, v6
	v_ashrrev_i32_e32 v13, 31, v12
	v_ashrrev_i32_e32 v15, 31, v14
	v_cndmask_b32_e32 v7, v221, v7, vcc
	v_lshlrev_b32_e32 v131, 2, v7
	v_xor_b32_e32 v7, 8, v221
	v_cmp_lt_i32_e32 vcc, v7, v6
	v_and_b32_e32 v116, 0xffffff00, v115
	v_and_b32_e32 v117, 63, v114
	v_lshrrev_b32_e32 v140, 6, v114
	v_lshlrev_b32_e32 v117, 4, v117
	v_lshl_add_u32 v117, v140, 2, v117
	v_add_u32_e32 v117, s61, v117
	v_cndmask_b32_e32 v7, v221, v7, vcc
	v_lshlrev_b32_e32 v132, 2, v7
	v_xor_b32_e32 v7, 16, v221
	v_cmp_lt_i32_e32 vcc, v7, v6
	v_lshlrev_b64 v[98:99], 13, v[8:9]
	v_lshlrev_b64 v[100:101], 13, v[10:11]
	v_cndmask_b32_e32 v7, v221, v7, vcc
	v_lshlrev_b32_e32 v133, 2, v7
	v_xor_b32_e32 v7, 32, v221
	v_cmp_lt_i32_e32 vcc, v7, v6
	v_lshlrev_b64 v[102:103], 13, v[12:13]
	v_lshlrev_b64 v[104:105], 13, v[14:15]
	v_cndmask_b32_e32 v6, v221, v7, vcc
	v_sub_co_u32_e32 v4, vcc, v5, v4
	v_lshlrev_b32_e32 v134, 2, v6
	s_nop 0
	v_subb_co_u32_e64 v5, s[0:1], 0, 0, vcc
	v_lshl_add_u64 v[4:5], v[4:5], 0, s[8:9]
	v_lshlrev_b64 v[4:5], 1, v[4:5]
	v_lshl_add_u64 v[106:107], v[0:1], 0, v[4:5]
	v_lshl_add_u64 v[0:1], v[2:3], 0, v[4:5]
	s_mov_b64 s[0:1], 0x1eb04000
	v_lshl_add_u64 v[108:109], v[0:1], 0, s[0:1]
	v_lshlrev_b32_e32 v0, 1, v114
	v_add_u32_e32 v135, 0, v115
	v_add_u32_e32 v136, 0xfffffe00, v114
	v_sub_u32_e32 v137, 0x2200, v0
	v_add_u32_e32 v138, 0x2200, v0
	v_sub_u32_e32 v139, 0, v114
	v_add_u32_e32 v140, s10, v115
	s_mov_b32 s6, s90
	v_readlane_b32 s69, v251, 37
	v_readlane_b32 s70, v251, 38
	v_readlane_b32 s71, v251, 39
	v_readlane_b32 s72, v251, 40
	v_readlane_b32 s73, v251, 41
	v_readlane_b32 s76, v251, 44
	v_readlane_b32 s77, v251, 45
	v_readlane_b32 s78, v251, 46
	v_readlane_b32 s79, v251, 47
	v_readlane_b32 s80, v251, 48
	v_readlane_b32 s81, v251, 49
	v_readlane_b32 s82, v251, 50
	v_readlane_b32 s83, v251, 51
	s_branch .LBB0_606

; __device__ __forceinline__ void hy_conv_item(const Ctx& C, int l, int c) {
;     ...
;     for (int k = 0; k < 8; ++k) { const int t = tid + NTHR * k; const f32x4* hr = (const f32x4*)(hdn + (size_t)t * 64);
;         float a0 = 0.f, a1 = 0.f, a2 = 0.f, a3 = 0.f;
; #pragma unroll 1
;         for (int j8 = 0; j8 < 16; j8 += 8) {
;         f32x4 hrow[8];
; #pragma unroll
;         for (int j4 = 0; j4 < 8; ++j4) hrow[j4] = hr[j8 + j4];
; #pragma unroll
;         for (int jj4 = 0; jj4 < 8; ++jj4) { const f32x4 hv = hrow[jj4]; const int j4 = j8 + jj4;
;             const f32x4 q0 = *(const f32x4*)(w3s + 4 * j4), q1 = *(const f32x4*)(w3s + 64 + 4 * j4), q2 = *(const f32x4*)(w3s + 128 + 4 * j4), q3 = *(const f32x4*)(w3s + 192 + 4 * j4);
;             a0 += hv.x * q0.x + hv.y * q0.y + hv.z * q0.z + hv.w * q0.w; a1 += hv.x * q1.x + hv.y * q1.y + hv.z * q1.z + hv.w * q1.w;
;             a2 += hv.x * q2.x + hv.y * q2.y + hv.z * q2.z + hv.w * q2.w; a3 += hv.x * q3.x + hv.y * q3.y + hv.z * q3.z + hv.w * q3.w; } }
.LBB0_612:
	v_lshl_add_u32 v8, s7, 9, v114
	v_ashrrev_i32_e32 v9, 31, v8
	v_lshlrev_b64 v[0:1], 8, v[8:9]
	v_lshl_add_u64 v[10:11], s[4:5], 0, v[0:1]
	s_mov_b64 s[0:1], -1
	s_mov_b32 s36, 0
	v_mov_b32_e32 v14, 0
	v_mov_b32_e32 v15, v17
	v_mov_b32_e32 v12, 0
	v_mov_b32_e32 v13, v17
	global_load_dwordx4 v[18:21], v[10:11], off
	global_load_dwordx4 v[22:25], v[10:11], off offset:16
	global_load_dwordx4 v[26:29], v[10:11], off offset:32
	global_load_dwordx4 v[30:33], v[10:11], off offset:48
	global_load_dwordx4 v[34:37], v[10:11], off offset:64
	global_load_dwordx4 v[38:41], v[10:11], off offset:80
	global_load_dwordx4 v[42:45], v[10:11], off offset:96
	global_load_dwordx4 v[46:49], v[10:11], off offset:112
	global_load_dwordx4 v[192:195], v[10:11], off offset:128
	global_load_dwordx4 v[196:199], v[10:11], off offset:144
	global_load_dwordx4 v[200:203], v[10:11], off offset:160
	global_load_dwordx4 v[204:207], v[10:11], off offset:176
	global_load_dwordx4 v[208:211], v[10:11], off offset:192
	global_load_dwordx4 v[212:215], v[10:11], off offset:208
	global_load_dwordx4 v[228:231], v[10:11], off offset:224
	global_load_dwordx4 v[232:235], v[10:11], off offset:240
	v_mov_b32_e32 v9, s61
	ds_read_b128 v[142:145], v9
	ds_read_b128 v[146:149], v9 offset:16
	ds_read_b128 v[150:153], v9 offset:32
	ds_read_b128 v[154:157], v9 offset:48
	ds_read_b128 v[158:161], v9 offset:64
	ds_read_b128 v[162:165], v9 offset:80
	ds_read_b128 v[166:169], v9 offset:96
	ds_read_b128 v[170:173], v9 offset:112
	ds_read_b128 v[174:177], v9 offset:128
	ds_read_b128 v[178:181], v9 offset:144
	ds_read_b128 v[50:53], v9 offset:160
	ds_read_b128 v[54:57], v9 offset:176
	s_waitcnt vmcnt(15) lgkmcnt(11)
	v_pk_fma_f32 v[14:15], v[18:19], v[142:143], v[14:15] op_sel_hi:[0,1,1]
	v_pk_fma_f32 v[12:13], v[18:19], v[144:145], v[12:13] op_sel_hi:[0,1,1]
	ds_read_b128 v[142:145], v9 offset:192
	s_waitcnt lgkmcnt(11)
	v_pk_mul_f32 v[58:59], v[18:19], v[146:147] op_sel:[1,0] op_sel_hi:[1,1]
	v_pk_mul_f32 v[60:61], v[18:19], v[148:149] op_sel:[1,0] op_sel_hi:[1,1]
	ds_read_b128 v[146:149], v9 offset:208
	s_waitcnt lgkmcnt(11)
	v_pk_fma_f32 v[14:15], v[20:21], v[150:151], v[14:15] op_sel_hi:[0,1,1]
	v_pk_fma_f32 v[12:13], v[20:21], v[152:153], v[12:13] op_sel_hi:[0,1,1]
	ds_read_b128 v[150:153], v9 offset:224
	s_waitcnt lgkmcnt(11)
	v_pk_fma_f32 v[58:59], v[20:21], v[154:155], v[58:59] op_sel:[1,0,0] op_sel_hi:[1,1,1]
	v_pk_fma_f32 v[60:61], v[20:21], v[156:157], v[60:61] op_sel:[1,0,0] op_sel_hi:[1,1,1]
	ds_read_b128 v[154:157], v9 offset:240
	s_waitcnt vmcnt(14) lgkmcnt(11)
	v_pk_fma_f32 v[14:15], v[22:23], v[158:159], v[14:15] op_sel_hi:[0,1,1]
	v_pk_fma_f32 v[12:13], v[22:23], v[160:161], v[12:13] op_sel_hi:[0,1,1]
	ds_read_b128 v[158:161], v9 offset:256
	s_waitcnt lgkmcnt(11)
	v_pk_fma_f32 v[58:59], v[22:23], v[162:163], v[58:59] op_sel:[1,0,0] op_sel_hi:[1,1,1]
	v_pk_fma_f32 v[60:61], v[22:23], v[164:165], v[60:61] op_sel:[1,0,0] op_sel_hi:[1,1,1]
	ds_read_b128 v[162:165], v9 offset:272
	s_waitcnt lgkmcnt(11)
	v_pk_fma_f32 v[14:15], v[24:25], v[166:167], v[14:15] op_sel_hi:[0,1,1]
	v_pk_fma_f32 v[12:13], v[24:25], v[168:169], v[12:13] op_sel_hi:[0,1,1]
	ds_read_b128 v[166:169], v9 offset:288
	s_waitcnt lgkmcnt(11)
	v_pk_fma_f32 v[58:59], v[24:25], v[170:171], v[58:59] op_sel:[1,0,0] op_sel_hi:[1,1,1]
	v_pk_fma_f32 v[60:61], v[24:25], v[172:173], v[60:61] op_sel:[1,0,0] op_sel_hi:[1,1,1]
	ds_read_b128 v[170:173], v9 offset:304
	s_waitcnt vmcnt(13) lgkmcnt(11)
	v_pk_fma_f32 v[14:15], v[26:27], v[174:175], v[14:15] op_sel_hi:[0,1,1]
	v_pk_fma_f32 v[12:13], v[26:27], v[176:177], v[12:13] op_sel_hi:[0,1,1]
	ds_read_b128 v[174:177], v9 offset:320
	s_waitcnt lgkmcnt(11)
	v_pk_fma_f32 v[58:59], v[26:27], v[178:179], v[58:59] op_sel:[1,0,0] op_sel_hi:[1,1,1]
	v_pk_fma_f32 v[60:61], v[26:27], v[180:181], v[60:61] op_sel:[1,0,0] op_sel_hi:[1,1,1]
	ds_read_b128 v[178:181], v9 offset:336
	s_waitcnt lgkmcnt(11)
	v_pk_fma_f32 v[14:15], v[28:29], v[50:51], v[14:15] op_sel_hi:[0,1,1]
	v_pk_fma_f32 v[12:13], v[28:29], v[52:53], v[12:13] op_sel_hi:[0,1,1]
	ds_read_b128 v[50:53], v9 offset:352
	s_waitcnt lgkmcnt(11)
	v_pk_fma_f32 v[58:59], v[28:29], v[54:55], v[58:59] op_sel:[1,0,0] op_sel_hi:[1,1,1]
	v_pk_fma_f32 v[60:61], v[28:29], v[56:57], v[60:61] op_sel:[1,0,0] op_sel_hi:[1,1,1]
	ds_read_b128 v[54:57], v9 offset:368
	s_waitcnt vmcnt(12) lgkmcnt(11)
	v_pk_fma_f32 v[14:15], v[30:31], v[142:143], v[14:15] op_sel_hi:[0,1,1]
	v_pk_fma_f32 v[12:13], v[30:31], v[144:145], v[12:13] op_sel_hi:[0,1,1]
	ds_read_b128 v[142:145], v9 offset:384
	s_waitcnt lgkmcnt(11)
	v_pk_fma_f32 v[58:59], v[30:31], v[146:147], v[58:59] op_sel:[1,0,0] op_sel_hi:[1,1,1]
	v_pk_fma_f32 v[60:61], v[30:31], v[148:149], v[60:61] op_sel:[1,0,0] op_sel_hi:[1,1,1]
	ds_read_b128 v[146:149], v9 offset:400
	s_waitcnt lgkmcnt(11)
	v_pk_fma_f32 v[14:15], v[32:33], v[150:151], v[14:15] op_sel_hi:[0,1,1]
	v_pk_fma_f32 v[12:13], v[32:33], v[152:153], v[12:13] op_sel_hi:[0,1,1]
	ds_read_b128 v[150:153], v9 offset:416
	s_waitcnt lgkmcnt(11)
	v_pk_fma_f32 v[58:59], v[32:33], v[154:155], v[58:59] op_sel:[1,0,0] op_sel_hi:[1,1,1]
	v_pk_fma_f32 v[60:61], v[32:33], v[156:157], v[60:61] op_sel:[1,0,0] op_sel_hi:[1,1,1]
	ds_read_b128 v[154:157], v9 offset:432
	s_waitcnt vmcnt(11) lgkmcnt(11)
	v_pk_fma_f32 v[14:15], v[34:35], v[158:159], v[14:15] op_sel_hi:[0,1,1]
	v_pk_fma_f32 v[12:13], v[34:35], v[160:161], v[12:13] op_sel_hi:[0,1,1]
	ds_read_b128 v[158:161], v9 offset:448
	s_waitcnt lgkmcnt(11)
	v_pk_fma_f32 v[58:59], v[34:35], v[162:163], v[58:59] op_sel:[1,0,0] op_sel_hi:[1,1,1]
	v_pk_fma_f32 v[60:61], v[34:35], v[164:165], v[60:61] op_sel:[1,0,0] op_sel_hi:[1,1,1]
	ds_read_b128 v[162:165], v9 offset:464
	s_waitcnt lgkmcnt(11)
; __device__ __forceinline__ void hy_conv_item(const Ctx& C, int l, int c) {
;     ...
;     for (int k = 0; k < 8; ++k) { const int t = tid + NTHR * k; const f32x4* hr = (const f32x4*)(hdn + (size_t)t * 64);
;         float a0 = 0.f, a1 = 0.f, a2 = 0.f, a3 = 0.f;
; #pragma unroll 1
;         for (int j8 = 0; j8 < 16; j8 += 8) {
;         f32x4 hrow[8];
; #pragma unroll
;         for (int j4 = 0; j4 < 8; ++j4) hrow[j4] = hr[j8 + j4];
; #pragma unroll
;         for (int jj4 = 0; jj4 < 8; ++jj4) { const f32x4 hv = hrow[jj4]; const int j4 = j8 + jj4;
;             const f32x4 q0 = *(const f32x4*)(w3s + 4 * j4), q1 = *(const f32x4*)(w3s + 64 + 4 * j4), q2 = *(const f32x4*)(w3s + 128 + 4 * j4), q3 = *(const f32x4*)(w3s + 192 + 4 * j4);
;             a0 += hv.x * q0.x + hv.y * q0.y + hv.z * q0.z + hv.w * q0.w; a1 += hv.x * q1.x + hv.y * q1.y + hv.z * q1.z + hv.w * q1.w;
;             a2 += hv.x * q2.x + hv.y * q2.y + hv.z * q2.z + hv.w * q2.w; a3 += hv.x * q3.x + hv.y * q3.y + hv.z * q3.z + hv.w * q3.w; } }
	v_pk_fma_f32 v[14:15], v[36:37], v[166:167], v[14:15] op_sel_hi:[0,1,1]
	v_pk_fma_f32 v[12:13], v[36:37], v[168:169], v[12:13] op_sel_hi:[0,1,1]
	ds_read_b128 v[166:169], v9 offset:480
	s_waitcnt lgkmcnt(11)
	v_pk_fma_f32 v[58:59], v[36:37], v[170:171], v[58:59] op_sel:[1,0,0] op_sel_hi:[1,1,1]
	v_pk_fma_f32 v[60:61], v[36:37], v[172:173], v[60:61] op_sel:[1,0,0] op_sel_hi:[1,1,1]
	ds_read_b128 v[170:173], v9 offset:496
	s_waitcnt vmcnt(10) lgkmcnt(11)
	v_pk_fma_f32 v[14:15], v[38:39], v[174:175], v[14:15] op_sel_hi:[0,1,1]
	v_pk_fma_f32 v[12:13], v[38:39], v[176:177], v[12:13] op_sel_hi:[0,1,1]
	ds_read_b128 v[174:177], v9 offset:512
	s_waitcnt lgkmcnt(11)
	v_pk_fma_f32 v[58:59], v[38:39], v[178:179], v[58:59] op_sel:[1,0,0] op_sel_hi:[1,1,1]
	v_pk_fma_f32 v[60:61], v[38:39], v[180:181], v[60:61] op_sel:[1,0,0] op_sel_hi:[1,1,1]
	ds_read_b128 v[178:181], v9 offset:528
	s_waitcnt lgkmcnt(11)
	v_pk_fma_f32 v[14:15], v[40:41], v[50:51], v[14:15] op_sel_hi:[0,1,1]
	v_pk_fma_f32 v[12:13], v[40:41], v[52:53], v[12:13] op_sel_hi:[0,1,1]
	ds_read_b128 v[50:53], v9 offset:544
	s_waitcnt lgkmcnt(11)
	v_pk_fma_f32 v[58:59], v[40:41], v[54:55], v[58:59] op_sel:[1,0,0] op_sel_hi:[1,1,1]
	v_pk_fma_f32 v[60:61], v[40:41], v[56:57], v[60:61] op_sel:[1,0,0] op_sel_hi:[1,1,1]
	ds_read_b128 v[54:57], v9 offset:560
	s_waitcnt vmcnt(9) lgkmcnt(11)
	v_pk_fma_f32 v[14:15], v[42:43], v[142:143], v[14:15] op_sel_hi:[0,1,1]
	v_pk_fma_f32 v[12:13], v[42:43], v[144:145], v[12:13] op_sel_hi:[0,1,1]
	ds_read_b128 v[142:145], v9 offset:576
	s_waitcnt lgkmcnt(11)
	v_pk_fma_f32 v[58:59], v[42:43], v[146:147], v[58:59] op_sel:[1,0,0] op_sel_hi:[1,1,1]
	v_pk_fma_f32 v[60:61], v[42:43], v[148:149], v[60:61] op_sel:[1,0,0] op_sel_hi:[1,1,1]
	ds_read_b128 v[146:149], v9 offset:592
	s_waitcnt lgkmcnt(11)
	v_pk_fma_f32 v[14:15], v[44:45], v[150:151], v[14:15] op_sel_hi:[0,1,1]
	v_pk_fma_f32 v[12:13], v[44:45], v[152:153], v[12:13] op_sel_hi:[0,1,1]
	ds_read_b128 v[150:153], v9 offset:608
	s_waitcnt lgkmcnt(11)
	v_pk_fma_f32 v[58:59], v[44:45], v[154:155], v[58:59] op_sel:[1,0,0] op_sel_hi:[1,1,1]
	v_pk_fma_f32 v[60:61], v[44:45], v[156:157], v[60:61] op_sel:[1,0,0] op_sel_hi:[1,1,1]
	ds_read_b128 v[154:157], v9 offset:624
	s_waitcnt vmcnt(8) lgkmcnt(11)
	v_pk_fma_f32 v[14:15], v[46:47], v[158:159], v[14:15] op_sel_hi:[0,1,1]
	v_pk_fma_f32 v[12:13], v[46:47], v[160:161], v[12:13] op_sel_hi:[0,1,1]
	ds_read_b128 v[158:161], v9 offset:640
	s_waitcnt lgkmcnt(11)
	v_pk_fma_f32 v[58:59], v[46:47], v[162:163], v[58:59] op_sel:[1,0,0] op_sel_hi:[1,1,1]
	v_pk_fma_f32 v[60:61], v[46:47], v[164:165], v[60:61] op_sel:[1,0,0] op_sel_hi:[1,1,1]
	ds_read_b128 v[162:165], v9 offset:656
	s_waitcnt lgkmcnt(11)
	v_pk_fma_f32 v[14:15], v[48:49], v[166:167], v[14:15] op_sel_hi:[0,1,1]
	v_pk_fma_f32 v[12:13], v[48:49], v[168:169], v[12:13] op_sel_hi:[0,1,1]
	ds_read_b128 v[166:169], v9 offset:672
	s_waitcnt lgkmcnt(11)
	v_pk_fma_f32 v[58:59], v[48:49], v[170:171], v[58:59] op_sel:[1,0,0] op_sel_hi:[1,1,1]
	v_pk_fma_f32 v[60:61], v[48:49], v[172:173], v[60:61] op_sel:[1,0,0] op_sel_hi:[1,1,1]
	ds_read_b128 v[170:173], v9 offset:688
	s_waitcnt vmcnt(7) lgkmcnt(11)
	v_pk_fma_f32 v[14:15], v[192:193], v[174:175], v[14:15] op_sel_hi:[0,1,1]
	v_pk_fma_f32 v[12:13], v[192:193], v[176:177], v[12:13] op_sel_hi:[0,1,1]
	ds_read_b128 v[174:177], v9 offset:704
	s_waitcnt lgkmcnt(11)
	v_pk_fma_f32 v[58:59], v[192:193], v[178:179], v[58:59] op_sel:[1,0,0] op_sel_hi:[1,1,1]
	v_pk_fma_f32 v[60:61], v[192:193], v[180:181], v[60:61] op_sel:[1,0,0] op_sel_hi:[1,1,1]
	ds_read_b128 v[178:181], v9 offset:720
	s_waitcnt lgkmcnt(11)
	v_pk_fma_f32 v[14:15], v[194:195], v[50:51], v[14:15] op_sel_hi:[0,1,1]
	v_pk_fma_f32 v[12:13], v[194:195], v[52:53], v[12:13] op_sel_hi:[0,1,1]
	ds_read_b128 v[50:53], v9 offset:736
	s_waitcnt lgkmcnt(11)
	v_pk_fma_f32 v[58:59], v[194:195], v[54:55], v[58:59] op_sel:[1,0,0] op_sel_hi:[1,1,1]
	v_pk_fma_f32 v[60:61], v[194:195], v[56:57], v[60:61] op_sel:[1,0,0] op_sel_hi:[1,1,1]
	ds_read_b128 v[54:57], v9 offset:752
	s_waitcnt vmcnt(6) lgkmcnt(11)
	v_pk_fma_f32 v[14:15], v[196:197], v[142:143], v[14:15] op_sel_hi:[0,1,1]
	v_pk_fma_f32 v[12:13], v[196:197], v[144:145], v[12:13] op_sel_hi:[0,1,1]
	ds_read_b128 v[142:145], v9 offset:768
	s_waitcnt lgkmcnt(11)
	v_pk_fma_f32 v[58:59], v[196:197], v[146:147], v[58:59] op_sel:[1,0,0] op_sel_hi:[1,1,1]
	v_pk_fma_f32 v[60:61], v[196:197], v[148:149], v[60:61] op_sel:[1,0,0] op_sel_hi:[1,1,1]
	ds_read_b128 v[146:149], v9 offset:784
	s_waitcnt lgkmcnt(11)
	v_pk_fma_f32 v[14:15], v[198:199], v[150:151], v[14:15] op_sel_hi:[0,1,1]
	v_pk_fma_f32 v[12:13], v[198:199], v[152:153], v[12:13] op_sel_hi:[0,1,1]
	ds_read_b128 v[150:153], v9 offset:800
	s_waitcnt lgkmcnt(11)
	v_pk_fma_f32 v[58:59], v[198:199], v[154:155], v[58:59] op_sel:[1,0,0] op_sel_hi:[1,1,1]
	v_pk_fma_f32 v[60:61], v[198:199], v[156:157], v[60:61] op_sel:[1,0,0] op_sel_hi:[1,1,1]
	ds_read_b128 v[154:157], v9 offset:816
	s_waitcnt vmcnt(5) lgkmcnt(11)
	v_pk_fma_f32 v[14:15], v[200:201], v[158:159], v[14:15] op_sel_hi:[0,1,1]
	v_pk_fma_f32 v[12:13], v[200:201], v[160:161], v[12:13] op_sel_hi:[0,1,1]
	ds_read_b128 v[158:161], v9 offset:832
	s_waitcnt lgkmcnt(11)
	v_pk_fma_f32 v[58:59], v[200:201], v[162:163], v[58:59] op_sel:[1,0,0] op_sel_hi:[1,1,1]
	v_pk_fma_f32 v[60:61], v[200:201], v[164:165], v[60:61] op_sel:[1,0,0] op_sel_hi:[1,1,1]
	ds_read_b128 v[162:165], v9 offset:848
	s_waitcnt lgkmcnt(11)
	v_pk_fma_f32 v[14:15], v[202:203], v[166:167], v[14:15] op_sel_hi:[0,1,1]
	v_pk_fma_f32 v[12:13], v[202:203], v[168:169], v[12:13] op_sel_hi:[0,1,1]
	ds_read_b128 v[166:169], v9 offset:864
	s_waitcnt lgkmcnt(11)
; __device__ __forceinline__ void hy_conv_item(const Ctx& C, int l, int c) {
;     ...
;     for (int k = 0; k < 8; ++k) { const int t = tid + NTHR * k; const f32x4* hr = (const f32x4*)(hdn + (size_t)t * 64);
;         float a0 = 0.f, a1 = 0.f, a2 = 0.f, a3 = 0.f;
; #pragma unroll 1
;         for (int j8 = 0; j8 < 16; j8 += 8) {
;         f32x4 hrow[8];
; #pragma unroll
;         for (int j4 = 0; j4 < 8; ++j4) hrow[j4] = hr[j8 + j4];
; #pragma unroll
;         for (int jj4 = 0; jj4 < 8; ++jj4) { const f32x4 hv = hrow[jj4]; const int j4 = j8 + jj4;
;             const f32x4 q0 = *(const f32x4*)(w3s + 4 * j4), q1 = *(const f32x4*)(w3s + 64 + 4 * j4), q2 = *(const f32x4*)(w3s + 128 + 4 * j4), q3 = *(const f32x4*)(w3s + 192 + 4 * j4);
;             a0 += hv.x * q0.x + hv.y * q0.y + hv.z * q0.z + hv.w * q0.w; a1 += hv.x * q1.x + hv.y * q1.y + hv.z * q1.z + hv.w * q1.w;
;             a2 += hv.x * q2.x + hv.y * q2.y + hv.z * q2.z + hv.w * q2.w; a3 += hv.x * q3.x + hv.y * q3.y + hv.z * q3.z + hv.w * q3.w; } }
;         const float dec = __expf(-((float)t / 4095.f) * adelta);
;         a0 *= dec; a1 *= dec; a2 *= dec; a3 *= dec;
;         hft[t] = a0; hft[4096 + t] = a1; hft[8192 + t] = a2; hft[12288 + t] = a3;
;         ss[0] += a0 * a0; ss[1] += a1 * a1; ss[2] += a2 * a2; ss[3] += a3 * a3; }
; #pragma unroll
;     for (int q = 0; q < 4; ++q) { const float s_ = wave_sum(ss[q]); if (lane == 0) red[w * 4 + q] = s_; }
	v_pk_fma_f32 v[58:59], v[202:203], v[170:171], v[58:59] op_sel:[1,0,0] op_sel_hi:[1,1,1]
	v_pk_fma_f32 v[60:61], v[202:203], v[172:173], v[60:61] op_sel:[1,0,0] op_sel_hi:[1,1,1]
	ds_read_b128 v[170:173], v9 offset:880
	s_waitcnt vmcnt(4) lgkmcnt(11)
	v_pk_fma_f32 v[14:15], v[204:205], v[174:175], v[14:15] op_sel_hi:[0,1,1]
	v_pk_fma_f32 v[12:13], v[204:205], v[176:177], v[12:13] op_sel_hi:[0,1,1]
	ds_read_b128 v[174:177], v9 offset:896
	s_waitcnt lgkmcnt(11)
	v_pk_fma_f32 v[58:59], v[204:205], v[178:179], v[58:59] op_sel:[1,0,0] op_sel_hi:[1,1,1]
	v_pk_fma_f32 v[60:61], v[204:205], v[180:181], v[60:61] op_sel:[1,0,0] op_sel_hi:[1,1,1]
	ds_read_b128 v[178:181], v9 offset:912
	s_waitcnt lgkmcnt(11)
	v_pk_fma_f32 v[14:15], v[206:207], v[50:51], v[14:15] op_sel_hi:[0,1,1]
	v_pk_fma_f32 v[12:13], v[206:207], v[52:53], v[12:13] op_sel_hi:[0,1,1]
	ds_read_b128 v[50:53], v9 offset:928
	s_waitcnt lgkmcnt(11)
	v_pk_fma_f32 v[58:59], v[206:207], v[54:55], v[58:59] op_sel:[1,0,0] op_sel_hi:[1,1,1]
	v_pk_fma_f32 v[60:61], v[206:207], v[56:57], v[60:61] op_sel:[1,0,0] op_sel_hi:[1,1,1]
	ds_read_b128 v[54:57], v9 offset:944
	s_waitcnt vmcnt(3) lgkmcnt(11)
	v_pk_fma_f32 v[14:15], v[208:209], v[142:143], v[14:15] op_sel_hi:[0,1,1]
	v_pk_fma_f32 v[12:13], v[208:209], v[144:145], v[12:13] op_sel_hi:[0,1,1]
	ds_read_b128 v[142:145], v9 offset:960
	s_waitcnt lgkmcnt(11)
	v_pk_fma_f32 v[58:59], v[208:209], v[146:147], v[58:59] op_sel:[1,0,0] op_sel_hi:[1,1,1]
	v_pk_fma_f32 v[60:61], v[208:209], v[148:149], v[60:61] op_sel:[1,0,0] op_sel_hi:[1,1,1]
	ds_read_b128 v[146:149], v9 offset:976
	s_waitcnt lgkmcnt(11)
	v_pk_fma_f32 v[14:15], v[210:211], v[150:151], v[14:15] op_sel_hi:[0,1,1]
	v_pk_fma_f32 v[12:13], v[210:211], v[152:153], v[12:13] op_sel_hi:[0,1,1]
	ds_read_b128 v[150:153], v9 offset:992
	s_waitcnt lgkmcnt(11)
	v_pk_fma_f32 v[58:59], v[210:211], v[154:155], v[58:59] op_sel:[1,0,0] op_sel_hi:[1,1,1]
	v_pk_fma_f32 v[60:61], v[210:211], v[156:157], v[60:61] op_sel:[1,0,0] op_sel_hi:[1,1,1]
	ds_read_b128 v[154:157], v9 offset:1008
	s_waitcnt vmcnt(2) lgkmcnt(11)
	v_pk_fma_f32 v[14:15], v[212:213], v[158:159], v[14:15] op_sel_hi:[0,1,1]
	v_pk_fma_f32 v[12:13], v[212:213], v[160:161], v[12:13] op_sel_hi:[0,1,1]
	s_waitcnt lgkmcnt(10)
	v_pk_fma_f32 v[58:59], v[212:213], v[162:163], v[58:59] op_sel:[1,0,0] op_sel_hi:[1,1,1]
	v_pk_fma_f32 v[60:61], v[212:213], v[164:165], v[60:61] op_sel:[1,0,0] op_sel_hi:[1,1,1]
	s_waitcnt lgkmcnt(9)
	v_pk_fma_f32 v[14:15], v[214:215], v[166:167], v[14:15] op_sel_hi:[0,1,1]
	v_pk_fma_f32 v[12:13], v[214:215], v[168:169], v[12:13] op_sel_hi:[0,1,1]
	s_waitcnt lgkmcnt(8)
	v_pk_fma_f32 v[58:59], v[214:215], v[170:171], v[58:59] op_sel:[1,0,0] op_sel_hi:[1,1,1]
	v_pk_fma_f32 v[60:61], v[214:215], v[172:173], v[60:61] op_sel:[1,0,0] op_sel_hi:[1,1,1]
	s_waitcnt vmcnt(1) lgkmcnt(7)
	v_pk_fma_f32 v[14:15], v[228:229], v[174:175], v[14:15] op_sel_hi:[0,1,1]
	v_pk_fma_f32 v[12:13], v[228:229], v[176:177], v[12:13] op_sel_hi:[0,1,1]
	s_waitcnt lgkmcnt(6)
	v_pk_fma_f32 v[58:59], v[228:229], v[178:179], v[58:59] op_sel:[1,0,0] op_sel_hi:[1,1,1]
	v_pk_fma_f32 v[60:61], v[228:229], v[180:181], v[60:61] op_sel:[1,0,0] op_sel_hi:[1,1,1]
	s_waitcnt lgkmcnt(5)
	v_pk_fma_f32 v[14:15], v[230:231], v[50:51], v[14:15] op_sel_hi:[0,1,1]
	v_pk_fma_f32 v[12:13], v[230:231], v[52:53], v[12:13] op_sel_hi:[0,1,1]
	s_waitcnt lgkmcnt(4)
	v_pk_fma_f32 v[58:59], v[230:231], v[54:55], v[58:59] op_sel:[1,0,0] op_sel_hi:[1,1,1]
	v_pk_fma_f32 v[60:61], v[230:231], v[56:57], v[60:61] op_sel:[1,0,0] op_sel_hi:[1,1,1]
	s_waitcnt vmcnt(0) lgkmcnt(3)
	v_pk_fma_f32 v[14:15], v[232:233], v[142:143], v[14:15] op_sel_hi:[0,1,1]
	v_pk_fma_f32 v[12:13], v[232:233], v[144:145], v[12:13] op_sel_hi:[0,1,1]
	s_waitcnt lgkmcnt(2)
	v_pk_fma_f32 v[58:59], v[232:233], v[146:147], v[58:59] op_sel:[1,0,0] op_sel_hi:[1,1,1]
	v_pk_fma_f32 v[60:61], v[232:233], v[148:149], v[60:61] op_sel:[1,0,0] op_sel_hi:[1,1,1]
	s_waitcnt lgkmcnt(1)
	v_pk_fma_f32 v[14:15], v[234:235], v[150:151], v[14:15] op_sel_hi:[0,1,1]
	v_pk_fma_f32 v[12:13], v[234:235], v[152:153], v[12:13] op_sel_hi:[0,1,1]
	s_waitcnt lgkmcnt(0)
	v_pk_fma_f32 v[58:59], v[234:235], v[154:155], v[58:59] op_sel:[1,0,0] op_sel_hi:[1,1,1]
	v_pk_fma_f32 v[60:61], v[234:235], v[156:157], v[60:61] op_sel:[1,0,0] op_sel_hi:[1,1,1]
	v_pk_add_f32 v[14:15], v[14:15], v[58:59]
	v_pk_add_f32 v[12:13], v[12:13], v[60:61]
	v_cvt_f32_i32_e32 v0, v8
	s_add_i32 s7, s7, 1
	s_cmp_eq_u32 s7, 8
	v_rcp_f32_e32 v1, s22
	s_nop 0
	v_mul_f32_e32 v0, v0, v1
	v_mul_f32_e32 v0, v16, v0
	v_mul_f32_e32 v0, 0x3fb8aa3b, v0
	v_exp_f32_e32 v0, v0
	v_lshl_add_u32 v1, v8, 2, 0
	v_add_u32_e32 v8, 0x11000, v1
	v_pk_mul_f32 v[2:3], v[0:1], v[14:15] op_sel_hi:[0,1]
	v_pk_mul_f32 v[0:1], v[0:1], v[12:13] op_sel_hi:[0,1]
	v_pk_fma_f32 v[6:7], v[2:3], v[2:3], v[6:7]
	v_pk_fma_f32 v[4:5], v[0:1], v[0:1], v[4:5]
	ds_write2st64_b32 v8, v2, v3 offset1:64
	ds_write2st64_b32 v8, v0, v1 offset0:128 offset1:192
	s_cbranch_scc0 .LBB0_612
	ds_bpermute_b32 v0, v64, v6
	s_waitcnt lgkmcnt(0)
	v_add_f32_e32 v0, v6, v0
	ds_bpermute_b32 v1, v130, v0
	s_waitcnt lgkmcnt(0)
	v_add_f32_e32 v0, v0, v1
	ds_bpermute_b32 v1, v131, v0
	s_waitcnt lgkmcnt(0)
	v_add_f32_e32 v0, v0, v1
	ds_bpermute_b32 v1, v132, v0
	s_waitcnt lgkmcnt(0)
	v_add_f32_e32 v0, v0, v1
	ds_bpermute_b32 v1, v133, v0
	s_waitcnt lgkmcnt(0)
	v_add_f32_e32 v0, v0, v1
	ds_bpermute_b32 v1, v134, v0
	s_and_saveexec_b64 s[0:1], s[46:47]
	s_cbranch_execz .LBB0_617
	s_add_i32 s7, s12, 0
	s_add_i32 s7, s7, 0x25080
	s_waitcnt lgkmcnt(0)
	v_add_f32_e32 v0, v0, v1
	v_mov_b32_e32 v1, s7
	ds_write_b32 v1, v0
